# v46 + P6: SS1 row statistics loaded before the K-loop (2 loads/wave) and redistributed by ds_bpermute in EpiAct (no VMEM wait in the epilogue)
# speedup vs baseline: 1.0012x; 1.0012x over previous
; #define PG8_STAGE(bufoff, gbase, voff) do { _Pragma("unroll") for (int _i = 0; _i < 2; ++_i) \
;         __builtin_amdgcn_global_load_lds((const unsigned*)((const char*)(gbase) + (voff)[_i]), (PG8_LAS unsigned*)(lds + (bufoff) + ldsw + _i * 8192), 16, 0, 0); } while (0)
; #define PG8_LDA(dst, b, h) do { _Pragma("unroll") for (int m = 0; m < 4; ++m) _Pragma("unroll") for (int k = 0; k < 2; ++k) dst[m][k] = *(const PG8_LAS bf16x8*)(lds + PG8_SA(b, h) + aoff + m * 2048 + k * 1024); } while (0)
; #define PG8_LDB(dst, b, h) do { _Pragma("unroll") for (int n = 0; n < 2; ++n) _Pragma("unroll") for (int k = 0; k < 2; ++k) dst[n][k] = *(const PG8_LAS bf16x8*)(lds + PG8_SB(b, h) + boff + n * 2048 + k * 1024); } while (0)
; #define PG8_MMA(ai, bj, At, Bt) do { __builtin_amdgcn_s_setprio(1); _Pragma("unroll") for (int m = 0; m < 4; ++m) _Pragma("unroll") for (int n = 0; n < 2; ++n) _Pragma("unroll") for (int k = 0; k < 2; ++k) \
;         acc[ai][bj][m][n] = __builtin_amdgcn_mfma_f32_16x16x32_bf16(Bt[n][k], At[m][k], acc[ai][bj][m][n], 0, 0, 0); __builtin_amdgcn_s_setprio(0); } while (0)
; #define PG8_BAR __builtin_amdgcn_s_barrier()
; template <class Epi, class Sched, bool ALIGN_EPI = false, bool SP2 = false, bool AGM = false  >
; __device__ __forceinline__ void gemm_phase(PG8_LAS unsigned char* lds, const Gemm g, const Sched& S, const Epi& E) {
;     ...
;             PG8_LDB(B0, 0, 0); PG8_LDB(B1, 0, 1); PG8_SCHED; PG8_LDA(At, 0, 0); PG8_STAGE(PG8_SA(1, 1), a1 + hstepA, voffA);
;             PG8_WAIT_V(8); PG8_WAIT_L(0); PG8_BAR; PG8_MMA(0, 0, At, B0); PG8_MMA(0, 1, At, B1); PG8_BAR; PG8_SCHED;
;             PG8_LDA(At, 0, 1); PG8_STAGE(PG8_SB(0, 0), b2, voffB); PG8_STAGE(PG8_SB(0, 1), b2 + hstep, voffB); PG8_STAGE(PG8_SA(0, 0), a2, voffA);
;             PG8_WAIT_V(8); PG8_WAIT_L(0); PG8_BAR; PG8_MMA(1, 0, At, B0); PG8_MMA(1, 1, At, B1); PG8_BAR; PG8_SCHED;
;             PG8_LDB(B0, 1, 0); PG8_LDB(B1, 1, 1); PG8_SCHED; PG8_LDA(At, 1, 0); PG8_STAGE(PG8_SA(0, 1), a2 + hstepA, voffA);
;             PG8_WAIT_V(8); PG8_WAIT_L(0); PG8_BAR; PG8_MMA(0, 0, At, B0); PG8_MMA(0, 1, At, B1); PG8_BAR; PG8_SCHED;
;     __device__ __forceinline__ void operator()(const pg8::f32x4 (&acc)[2][2][4][2], const Unit& u, int wr, int wc, int fr, int fq) const {
;     ...
;             for (int m = 0; m < 4; ++m) { const int rg = ai * HALF + m * 16; const float rs = rstd_of(SS1[row0 + rg + fr]);
.LBB0_876:
	s_ashr_i32 s23, s22, 31
	s_lshl_b64 s[24:25], s[22:23], 19
	s_add_u32 s24, s46, s24
	s_addc_u32 s25, s47, s25
	s_and_b64 s[26:27], s[0:1], exec
	s_cselect_b32 s23, s25, s29
	s_cselect_b32 s64, s24, s28
	s_ashr_i32 s21, s20, 31
	s_lshl_b64 s[26:27], s[20:21], 19
	s_add_u32 s26, s10, s26
	s_addc_u32 s27, s11, s27
	s_and_b64 s[34:35], s[0:1], exec
	s_cselect_b32 s21, s27, s31
	s_cselect_b32 s65, s26, s30
	s_add_u32 s28, s28, 0x40080
	s_addc_u32 s29, s29, 0
	s_add_u32 s66, s30, 0x100
	s_addc_u32 s67, s31, 0
	s_mov_b32 s68, -2
	s_waitcnt vmcnt(0)
	v_and_b32_e32 v236, 63, v0
	v_lshl_add_u32 v236, s4, 8, v236
	v_add_u32_e32 v236, s42, v236
	v_lshlrev_b32_e32 v236, 2, v236
	global_load_dword v234, v236, s[14:15]
	global_load_dword v235, v236, s[14:15] offset:512
	s_waitcnt lgkmcnt(0)
	ds_read_b128 v[148:151], v156
	ds_read_b128 v[164:167], v156 offset:1024
	ds_read_b128 v[168:171], v156 offset:2048
	ds_read_b128 v[172:175], v156 offset:3072
	ds_read_b128 v[176:179], v157
	ds_read_b128 v[180:183], v157 offset:1024
	ds_read_b128 v[184:187], v157 offset:2048
	ds_read_b128 v[188:191], v157 offset:3072
	s_add_u32 s30, s28, 0xfffc0080
	s_addc_u32 s31, s29, -1
	s_cmp_eq_u32 s68, 12
	s_cselect_b32 s35, s23, s31
	s_cselect_b32 s34, s64, s30
	s_cselect_b32 s31, s21, s67
	s_cselect_b32 s30, s65, s66
	v_lshl_add_u64 v[224:225], s[28:29], 0, v[140:141]
	s_add_i32 m0, s37, 0xc000
	ds_read_b128 v[192:195], v158
	ds_read_b128 v[196:199], v158 offset:1024
	ds_read_b128 v[200:203], v158 offset:2048
	ds_read_b128 v[204:207], v158 offset:3072
	ds_read_b128 v[208:211], v158 offset:4096
	ds_read_b128 v[212:215], v158 offset:5120
	ds_read_b128 v[216:219], v158 offset:6144
	ds_read_b128 v[220:223], v158 offset:7168
	global_load_lds_dwordx4 v[224:225], off
	v_lshl_add_u64 v[224:225], s[28:29], 0, v[142:143]
	s_add_i32 m0, s37, 0xe000
	s_nop 0
	global_load_lds_dwordx4 v[224:225], off
	s_waitcnt vmcnt(8)
	s_waitcnt lgkmcnt(0)
	s_barrier
	s_setprio 1
	v_mfma_f32_16x16x32_bf16 v[126:129], v[148:151], v[192:195], 0
	v_mfma_f32_16x16x32_bf16 v[122:125], v[168:171], v[192:195], 0
	v_mfma_f32_16x16x32_bf16 v[110:113], v[148:151], v[200:203], 0
	v_mfma_f32_16x16x32_bf16 v[106:109], v[168:171], v[200:203], 0
	v_mfma_f32_16x16x32_bf16 v[94:97], v[148:151], v[208:211], 0
	v_mfma_f32_16x16x32_bf16 v[90:93], v[168:171], v[208:211], 0
	v_mfma_f32_16x16x32_bf16 v[78:81], v[148:151], v[216:219], 0
	v_mfma_f32_16x16x32_bf16 v[74:77], v[168:171], v[216:219], 0
	v_mfma_f32_16x16x32_bf16 v[126:129], v[164:167], v[196:199], v[126:129]
	v_mfma_f32_16x16x32_bf16 v[122:125], v[172:175], v[196:199], v[122:125]
	v_mfma_f32_16x16x32_bf16 v[110:113], v[164:167], v[204:207], v[110:113]
	v_mfma_f32_16x16x32_bf16 v[106:109], v[172:175], v[204:207], v[106:109]
	v_mfma_f32_16x16x32_bf16 v[94:97], v[164:167], v[212:215], v[94:97]
	v_mfma_f32_16x16x32_bf16 v[90:93], v[172:175], v[212:215], v[90:93]
	v_mfma_f32_16x16x32_bf16 v[78:81], v[164:167], v[220:223], v[78:81]
	v_mfma_f32_16x16x32_bf16 v[74:77], v[172:175], v[220:223], v[74:77]
	s_setprio 0
	s_setprio 1
	v_mfma_f32_16x16x32_bf16 v[118:121], v[176:179], v[192:195], 0
	v_mfma_f32_16x16x32_bf16 v[114:117], v[184:187], v[192:195], 0
	v_mfma_f32_16x16x32_bf16 v[102:105], v[176:179], v[200:203], 0
	v_mfma_f32_16x16x32_bf16 v[98:101], v[184:187], v[200:203], 0
	v_mfma_f32_16x16x32_bf16 v[86:89], v[176:179], v[208:211], 0
	v_mfma_f32_16x16x32_bf16 v[82:85], v[184:187], v[208:211], 0
	v_mfma_f32_16x16x32_bf16 v[70:73], v[176:179], v[216:219], 0
	v_mfma_f32_16x16x32_bf16 v[66:69], v[184:187], v[216:219], 0
	v_mfma_f32_16x16x32_bf16 v[118:121], v[180:183], v[196:199], v[118:121]
	v_mfma_f32_16x16x32_bf16 v[114:117], v[188:191], v[196:199], v[114:117]
	v_mfma_f32_16x16x32_bf16 v[102:105], v[180:183], v[204:207], v[102:105]
	v_mfma_f32_16x16x32_bf16 v[98:101], v[188:191], v[204:207], v[98:101]
	v_mfma_f32_16x16x32_bf16 v[86:89], v[180:183], v[212:215], v[86:89]
	v_mfma_f32_16x16x32_bf16 v[82:85], v[188:191], v[212:215], v[82:85]
	v_mfma_f32_16x16x32_bf16 v[70:73], v[180:183], v[220:223], v[70:73]
	v_mfma_f32_16x16x32_bf16 v[66:69], v[188:191], v[220:223], v[66:69]
	s_setprio 0
	s_barrier
	s_add_i32 s69, s53, s3
	v_lshl_add_u64 v[224:225], s[30:31], 0, v[134:135]
	s_mov_b32 m0, s69
	ds_read_b128 v[192:195], v158 offset:16384
	ds_read_b128 v[196:199], v158 offset:17408
	ds_read_b128 v[200:203], v158 offset:18432
	ds_read_b128 v[204:207], v158 offset:19456
	ds_read_b128 v[208:211], v158 offset:20480
	ds_read_b128 v[212:215], v158 offset:21504
	ds_read_b128 v[216:219], v158 offset:22528
	ds_read_b128 v[220:223], v158 offset:23552
	global_load_lds_dwordx4 v[224:225], off
	s_add_i32 m0, s69, 0x2000
	s_add_u32 s70, s30, 0x40000
	v_lshl_add_u64 v[226:227], s[30:31], 0, v[130:131]
	s_addc_u32 s71, s31, 0
	s_add_i32 s69, s54, s3
	global_load_lds_dwordx4 v[226:227], off
	v_lshl_add_u64 v[228:229], s[70:71], 0, v[134:135]
	s_mov_b32 m0, s69
	v_lshl_add_u64 v[230:231], s[34:35], 0, v[132:133]
	global_load_lds_dwordx4 v[228:229], off
	v_lshl_add_u64 v[228:229], s[70:71], 0, v[130:131]
	s_add_i32 m0, s69, 0x2000
	s_nop 0
	global_load_lds_dwordx4 v[228:229], off
	v_lshl_add_u64 v[228:229], s[34:35], 0, v[136:137]
	s_mov_b32 m0, s37
	s_nop 0
	global_load_lds_dwordx4 v[228:229], off
	s_mov_b32 m0, s38
	s_nop 0
	global_load_lds_dwordx4 v[230:231], off
	s_waitcnt vmcnt(8)
	s_waitcnt lgkmcnt(0)
	s_barrier
; #define PG8_STAGE(bufoff, gbase, voff) do { _Pragma("unroll") for (int _i = 0; _i < 2; ++_i) \
;         __builtin_amdgcn_global_load_lds((const unsigned*)((const char*)(gbase) + (voff)[_i]), (PG8_LAS unsigned*)(lds + (bufoff) + ldsw + _i * 8192), 16, 0, 0); } while (0)
; #define PG8_LDA(dst, b, h) do { _Pragma("unroll") for (int m = 0; m < 4; ++m) _Pragma("unroll") for (int k = 0; k < 2; ++k) dst[m][k] = *(const PG8_LAS bf16x8*)(lds + PG8_SA(b, h) + aoff + m * 2048 + k * 1024); } while (0)
; #define PG8_LDB(dst, b, h) do { _Pragma("unroll") for (int n = 0; n < 2; ++n) _Pragma("unroll") for (int k = 0; k < 2; ++k) dst[n][k] = *(const PG8_LAS bf16x8*)(lds + PG8_SB(b, h) + boff + n * 2048 + k * 1024); } while (0)
; #define PG8_MMA(ai, bj, At, Bt) do { __builtin_amdgcn_s_setprio(1); _Pragma("unroll") for (int m = 0; m < 4; ++m) _Pragma("unroll") for (int n = 0; n < 2; ++n) _Pragma("unroll") for (int k = 0; k < 2; ++k) \
;         acc[ai][bj][m][n] = __builtin_amdgcn_mfma_f32_16x16x32_bf16(Bt[n][k], At[m][k], acc[ai][bj][m][n], 0, 0, 0); __builtin_amdgcn_s_setprio(0); } while (0)
; #define PG8_WAIT_V(n) asm volatile("s_waitcnt vmcnt(" #n ")" ::: "memory")
; #define PG8_WAIT_L(n) asm volatile("s_waitcnt lgkmcnt(" #n ")" ::: "memory")
; #define PG8_BAR __builtin_amdgcn_s_barrier()
; #define PG8_SCHED __builtin_amdgcn_sched_barrier(0)
; template <class Epi, class Sched, bool ALIGN_EPI = false, bool SP2 = false, bool AGM = false  >
; __device__ __forceinline__ void gemm_phase(PG8_LAS unsigned char* lds, const Gemm g, const Sched& S, const Epi& E) {
;     ...
;             PG8_WAIT_V(8); PG8_WAIT_L(0); PG8_BAR; PG8_MMA(1, 0, At, B0); PG8_MMA(1, 1, At, B1); PG8_BAR; PG8_SCHED;
;             PG8_LDB(B0, 1, 0); PG8_LDB(B1, 1, 1); PG8_SCHED; PG8_LDA(At, 1, 0); PG8_STAGE(PG8_SA(0, 1), a2 + hstepA, voffA);
;             PG8_WAIT_V(8); PG8_WAIT_L(0); PG8_BAR; PG8_MMA(0, 0, At, B0); PG8_MMA(0, 1, At, B1); PG8_BAR; PG8_SCHED;
	s_setprio 1
	v_mfma_f32_16x16x32_bf16 v[62:65], v[148:151], v[192:195], 0
	v_mfma_f32_16x16x32_bf16 v[58:61], v[168:171], v[192:195], 0
	v_mfma_f32_16x16x32_bf16 v[46:49], v[148:151], v[200:203], 0
	v_mfma_f32_16x16x32_bf16 v[42:45], v[168:171], v[200:203], 0
	v_mfma_f32_16x16x32_bf16 v[30:33], v[148:151], v[208:211], 0
	v_mfma_f32_16x16x32_bf16 v[26:29], v[168:171], v[208:211], 0
	v_mfma_f32_16x16x32_bf16 v[14:17], v[148:151], v[216:219], 0
	v_mfma_f32_16x16x32_bf16 v[10:13], v[168:171], v[216:219], 0
	v_mfma_f32_16x16x32_bf16 v[62:65], v[164:167], v[196:199], v[62:65]
	v_mfma_f32_16x16x32_bf16 v[58:61], v[172:175], v[196:199], v[58:61]
	v_mfma_f32_16x16x32_bf16 v[46:49], v[164:167], v[204:207], v[46:49]
	v_mfma_f32_16x16x32_bf16 v[42:45], v[172:175], v[204:207], v[42:45]
	v_mfma_f32_16x16x32_bf16 v[30:33], v[164:167], v[212:215], v[30:33]
	v_mfma_f32_16x16x32_bf16 v[26:29], v[172:175], v[212:215], v[26:29]
	v_mfma_f32_16x16x32_bf16 v[14:17], v[164:167], v[220:223], v[14:17]
	v_mfma_f32_16x16x32_bf16 v[10:13], v[172:175], v[220:223], v[10:13]
	s_setprio 0
	s_setprio 1
	v_mfma_f32_16x16x32_bf16 v[54:57], v[176:179], v[192:195], 0
	v_mfma_f32_16x16x32_bf16 v[50:53], v[184:187], v[192:195], 0
	v_mfma_f32_16x16x32_bf16 v[38:41], v[176:179], v[200:203], 0
	v_mfma_f32_16x16x32_bf16 v[34:37], v[184:187], v[200:203], 0
	v_mfma_f32_16x16x32_bf16 v[22:25], v[176:179], v[208:211], 0
	v_mfma_f32_16x16x32_bf16 v[18:21], v[184:187], v[208:211], 0
	v_mfma_f32_16x16x32_bf16 v[6:9], v[176:179], v[216:219], 0
	v_mfma_f32_16x16x32_bf16 v[2:5], v[184:187], v[216:219], 0
	v_mfma_f32_16x16x32_bf16 v[54:57], v[180:183], v[196:199], v[54:57]
	v_mfma_f32_16x16x32_bf16 v[50:53], v[188:191], v[196:199], v[50:53]
	v_mfma_f32_16x16x32_bf16 v[38:41], v[180:183], v[204:207], v[38:41]
	v_mfma_f32_16x16x32_bf16 v[34:37], v[188:191], v[204:207], v[34:37]
	v_mfma_f32_16x16x32_bf16 v[22:25], v[180:183], v[212:215], v[22:25]
	v_mfma_f32_16x16x32_bf16 v[18:21], v[188:191], v[212:215], v[18:21]
	v_mfma_f32_16x16x32_bf16 v[6:9], v[180:183], v[220:223], v[6:9]
	v_mfma_f32_16x16x32_bf16 v[2:5], v[188:191], v[220:223], v[2:5]
	s_setprio 0
	s_barrier
	s_add_i32 s69, 0, 0x18000
	s_add_i32 s70, 0, 0x1c000
	v_add_u32_e32 v172, s69, v155
	v_add_u32_e32 v188, s70, v155
	ds_read_b128 v[148:151], v172
	ds_read_b128 v[164:167], v172 offset:1024
	ds_read_b128 v[168:171], v172 offset:2048
	ds_read_b128 v[172:175], v172 offset:3072
	ds_read_b128 v[176:179], v188
	ds_read_b128 v[180:183], v188 offset:1024
	ds_read_b128 v[184:187], v188 offset:2048
	ds_read_b128 v[188:191], v188 offset:3072
	s_add_u32 s34, s34, 0x40000
	s_addc_u32 s35, s35, 0
	s_mov_b32 m0, s39
	v_lshl_add_u64 v[232:233], s[34:35], 0, v[136:137]
	ds_read_b128 v[192:195], v158 offset:32768
	ds_read_b128 v[196:199], v158 offset:33792
	ds_read_b128 v[200:203], v158 offset:34816
	ds_read_b128 v[204:207], v158 offset:35840
	ds_read_b128 v[208:211], v158 offset:36864
	ds_read_b128 v[212:215], v158 offset:37888
	ds_read_b128 v[216:219], v158 offset:38912
	ds_read_b128 v[220:223], v158 offset:39936
	global_load_lds_dwordx4 v[232:233], off
	v_lshl_add_u64 v[232:233], s[34:35], 0, v[132:133]
	s_mov_b32 m0, s40
	s_nop 0
	global_load_lds_dwordx4 v[232:233], off
	s_waitcnt vmcnt(8)
	s_waitcnt lgkmcnt(0)
	s_barrier
	s_setprio 1
	v_mfma_f32_16x16x32_bf16 v[126:129], v[148:151], v[192:195], v[126:129]
	v_mfma_f32_16x16x32_bf16 v[122:125], v[168:171], v[192:195], v[122:125]
	v_mfma_f32_16x16x32_bf16 v[110:113], v[148:151], v[200:203], v[110:113]
	v_mfma_f32_16x16x32_bf16 v[106:109], v[168:171], v[200:203], v[106:109]
	v_mfma_f32_16x16x32_bf16 v[94:97], v[148:151], v[208:211], v[94:97]
	v_mfma_f32_16x16x32_bf16 v[90:93], v[168:171], v[208:211], v[90:93]
	v_mfma_f32_16x16x32_bf16 v[78:81], v[148:151], v[216:219], v[78:81]
	v_mfma_f32_16x16x32_bf16 v[74:77], v[168:171], v[216:219], v[74:77]
	v_mfma_f32_16x16x32_bf16 v[126:129], v[164:167], v[196:199], v[126:129]
	v_mfma_f32_16x16x32_bf16 v[122:125], v[172:175], v[196:199], v[122:125]
	v_mfma_f32_16x16x32_bf16 v[110:113], v[164:167], v[204:207], v[110:113]
	v_mfma_f32_16x16x32_bf16 v[106:109], v[172:175], v[204:207], v[106:109]
	v_mfma_f32_16x16x32_bf16 v[94:97], v[164:167], v[212:215], v[94:97]
	v_mfma_f32_16x16x32_bf16 v[90:93], v[172:175], v[212:215], v[90:93]
	v_mfma_f32_16x16x32_bf16 v[78:81], v[164:167], v[220:223], v[78:81]
	v_mfma_f32_16x16x32_bf16 v[74:77], v[172:175], v[220:223], v[74:77]
	s_setprio 0
	s_setprio 1
	v_mfma_f32_16x16x32_bf16 v[118:121], v[176:179], v[192:195], v[118:121]
	v_mfma_f32_16x16x32_bf16 v[114:117], v[184:187], v[192:195], v[114:117]
	v_mfma_f32_16x16x32_bf16 v[102:105], v[176:179], v[200:203], v[102:105]
	v_mfma_f32_16x16x32_bf16 v[98:101], v[184:187], v[200:203], v[98:101]
	v_mfma_f32_16x16x32_bf16 v[86:89], v[176:179], v[208:211], v[86:89]
	v_mfma_f32_16x16x32_bf16 v[82:85], v[184:187], v[208:211], v[82:85]
	v_mfma_f32_16x16x32_bf16 v[70:73], v[176:179], v[216:219], v[70:73]
	v_mfma_f32_16x16x32_bf16 v[66:69], v[184:187], v[216:219], v[66:69]
	v_mfma_f32_16x16x32_bf16 v[118:121], v[180:183], v[196:199], v[118:121]
	v_mfma_f32_16x16x32_bf16 v[114:117], v[188:191], v[196:199], v[114:117]
	v_mfma_f32_16x16x32_bf16 v[102:105], v[180:183], v[204:207], v[102:105]
	v_mfma_f32_16x16x32_bf16 v[98:101], v[188:191], v[204:207], v[98:101]
	v_mfma_f32_16x16x32_bf16 v[86:89], v[180:183], v[212:215], v[86:89]
	v_mfma_f32_16x16x32_bf16 v[82:85], v[188:191], v[212:215], v[82:85]
	v_mfma_f32_16x16x32_bf16 v[70:73], v[180:183], v[220:223], v[70:73]
	v_mfma_f32_16x16x32_bf16 v[66:69], v[188:191], v[220:223], v[66:69]
	s_setprio 0
	s_barrier
; #define PG8_STAGE(bufoff, gbase, voff) do { _Pragma("unroll") for (int _i = 0; _i < 2; ++_i) \
;         __builtin_amdgcn_global_load_lds((const unsigned*)((const char*)(gbase) + (voff)[_i]), (PG8_LAS unsigned*)(lds + (bufoff) + ldsw + _i * 8192), 16, 0, 0); } while (0)
; #define PG8_LDA(dst, b, h) do { _Pragma("unroll") for (int m = 0; m < 4; ++m) _Pragma("unroll") for (int k = 0; k < 2; ++k) dst[m][k] = *(const PG8_LAS bf16x8*)(lds + PG8_SA(b, h) + aoff + m * 2048 + k * 1024); } while (0)
; #define PG8_MMA(ai, bj, At, Bt) do { __builtin_amdgcn_s_setprio(1); _Pragma("unroll") for (int m = 0; m < 4; ++m) _Pragma("unroll") for (int n = 0; n < 2; ++n) _Pragma("unroll") for (int k = 0; k < 2; ++k) \
;         acc[ai][bj][m][n] = __builtin_amdgcn_mfma_f32_16x16x32_bf16(Bt[n][k], At[m][k], acc[ai][bj][m][n], 0, 0, 0); __builtin_amdgcn_s_setprio(0); } while (0)
; #define PG8_WAIT_V(n) asm volatile("s_waitcnt vmcnt(" #n ")" ::: "memory")
; #define PG8_WAIT_L(n) asm volatile("s_waitcnt lgkmcnt(" #n ")" ::: "memory")
; #define PG8_BAR __builtin_amdgcn_s_barrier()
; #define PG8_SCHED __builtin_amdgcn_sched_barrier(0)
; template <class Epi, class Sched, bool ALIGN_EPI = false, bool SP2 = false, bool AGM = false  >
; __device__ __forceinline__ void gemm_phase(PG8_LAS unsigned char* lds, const Gemm g, const Sched& S, const Epi& E) {
;     ...
;             PG8_LDA(At, 1, 1); PG8_STAGE(PG8_SB(1, 0), b3, voffB); PG8_STAGE(PG8_SB(1, 1), b3 + hstep, voffB); PG8_STAGE(PG8_SA(1, 0), a3, voffA);
;             PG8_WAIT_V(8); PG8_WAIT_L(0); PG8_BAR; PG8_MMA(1, 0, At, B0); PG8_MMA(1, 1, At, B1); PG8_BAR; PG8_SCHED;
	s_add_i32 s34, s69, s3
	v_lshl_add_u64 v[224:225], v[224:225], 0, s[16:17]
	s_mov_b32 m0, s34
	ds_read_b128 v[192:195], v158 offset:49152
	ds_read_b128 v[196:199], v158 offset:50176
	ds_read_b128 v[200:203], v158 offset:51200
	ds_read_b128 v[204:207], v158 offset:52224
	ds_read_b128 v[208:211], v158 offset:53248
	ds_read_b128 v[212:215], v158 offset:54272
	ds_read_b128 v[216:219], v158 offset:55296
	ds_read_b128 v[220:223], v158 offset:56320
	global_load_lds_dwordx4 v[224:225], off
	s_add_i32 m0, s34, 0x2000
	s_add_u32 s30, s30, 0x40080
	v_lshl_add_u64 v[224:225], v[226:227], 0, s[16:17]
	s_addc_u32 s31, s31, 0
	s_add_i32 s34, s70, s3
	global_load_lds_dwordx4 v[224:225], off
	v_lshl_add_u64 v[224:225], s[30:31], 0, v[134:135]
	s_mov_b32 m0, s34
	s_nop 0
	global_load_lds_dwordx4 v[224:225], off
	v_lshl_add_u64 v[224:225], s[30:31], 0, v[130:131]
	s_add_i32 m0, s34, 0x2000
	s_nop 0
	global_load_lds_dwordx4 v[224:225], off
	v_lshl_add_u64 v[224:225], v[228:229], 0, s[16:17]
	s_mov_b32 m0, s43
	s_nop 0
	global_load_lds_dwordx4 v[224:225], off
	v_lshl_add_u64 v[224:225], v[230:231], 0, s[16:17]
	s_mov_b32 m0, s44
	s_nop 0
	global_load_lds_dwordx4 v[224:225], off
	s_waitcnt vmcnt(8)
	s_waitcnt lgkmcnt(0)
	s_barrier
	s_setprio 1
	v_mfma_f32_16x16x32_bf16 v[62:65], v[148:151], v[192:195], v[62:65]
	v_mfma_f32_16x16x32_bf16 v[58:61], v[168:171], v[192:195], v[58:61]
	v_mfma_f32_16x16x32_bf16 v[46:49], v[148:151], v[200:203], v[46:49]
	v_mfma_f32_16x16x32_bf16 v[42:45], v[168:171], v[200:203], v[42:45]
	v_mfma_f32_16x16x32_bf16 v[30:33], v[148:151], v[208:211], v[30:33]
	v_mfma_f32_16x16x32_bf16 v[26:29], v[168:171], v[208:211], v[26:29]
	v_mfma_f32_16x16x32_bf16 v[14:17], v[148:151], v[216:219], v[14:17]
	v_mfma_f32_16x16x32_bf16 v[10:13], v[168:171], v[216:219], v[10:13]
	v_mfma_f32_16x16x32_bf16 v[62:65], v[164:167], v[196:199], v[62:65]
	v_mfma_f32_16x16x32_bf16 v[58:61], v[172:175], v[196:199], v[58:61]
	v_mfma_f32_16x16x32_bf16 v[46:49], v[164:167], v[204:207], v[46:49]
	v_mfma_f32_16x16x32_bf16 v[42:45], v[172:175], v[204:207], v[42:45]
	v_mfma_f32_16x16x32_bf16 v[30:33], v[164:167], v[212:215], v[30:33]
	v_mfma_f32_16x16x32_bf16 v[26:29], v[172:175], v[212:215], v[26:29]
	v_mfma_f32_16x16x32_bf16 v[14:17], v[164:167], v[220:223], v[14:17]
	v_mfma_f32_16x16x32_bf16 v[10:13], v[172:175], v[220:223], v[10:13]
	s_setprio 0
	s_setprio 1
	v_mfma_f32_16x16x32_bf16 v[54:57], v[176:179], v[192:195], v[54:57]
	v_mfma_f32_16x16x32_bf16 v[50:53], v[184:187], v[192:195], v[50:53]
	v_mfma_f32_16x16x32_bf16 v[38:41], v[176:179], v[200:203], v[38:41]
	v_mfma_f32_16x16x32_bf16 v[34:37], v[184:187], v[200:203], v[34:37]
	v_mfma_f32_16x16x32_bf16 v[22:25], v[176:179], v[208:211], v[22:25]
	v_mfma_f32_16x16x32_bf16 v[18:21], v[184:187], v[208:211], v[18:21]
	v_mfma_f32_16x16x32_bf16 v[6:9], v[176:179], v[216:219], v[6:9]
	v_mfma_f32_16x16x32_bf16 v[2:5], v[184:187], v[216:219], v[2:5]
	v_mfma_f32_16x16x32_bf16 v[54:57], v[180:183], v[196:199], v[54:57]
	v_mfma_f32_16x16x32_bf16 v[50:53], v[188:191], v[196:199], v[50:53]
	v_mfma_f32_16x16x32_bf16 v[38:41], v[180:183], v[204:207], v[38:41]
	v_mfma_f32_16x16x32_bf16 v[34:37], v[188:191], v[204:207], v[34:37]
	v_mfma_f32_16x16x32_bf16 v[22:25], v[180:183], v[212:215], v[22:25]
	v_mfma_f32_16x16x32_bf16 v[18:21], v[188:191], v[212:215], v[18:21]
	v_mfma_f32_16x16x32_bf16 v[6:9], v[180:183], v[220:223], v[6:9]
	v_mfma_f32_16x16x32_bf16 v[2:5], v[188:191], v[220:223], v[2:5]
	s_setprio 0
	s_barrier
	s_add_i32 s68, s68, 2
	s_add_u32 s28, s28, 0x100
	s_addc_u32 s29, s29, 0
	s_add_u32 s66, s66, 0x100
	s_addc_u32 s67, s67, 0
	s_cmp_gt_u32 s68, 13
	s_cbranch_scc1 .Lpeel_done_p6
	.p2align	6

; __device__ __forceinline__ unsigned cvt_pk_bf16(float lo, float hi) { unsigned r; asm volatile("v_cvt_pk_bf16_f32 %0, %1, %2" : "=v"(r) : "v"(lo), "v"(hi)); return r; }
; #define LAS __attribute__((address_space(3)))
; __device__ __forceinline__ float siluf_(float x) { return x * __builtin_amdgcn_rcpf(1.0f + __builtin_amdgcn_exp2f(-1.4426950408889634f * x)); }
; __device__ __forceinline__ float rstd_of(float ss) { return __builtin_amdgcn_rsqf(ss * (1.0f / DM) + EPS); }
;     __device__ __forceinline__ void operator()(const pg8::f32x4 (&acc)[2][2][4][2], const Unit& u, int wr, int wc, int fr, int fq) const {
;         const int row0 = u.pm * BM + wr * 64, lane = fr + 16 * fq, rr = lane >> 2, sl = lane & 3;
;         LAS unsigned char* W = scr + (wr * 4 + wc) * 2048;
;         bf16* outp = ACT + (size_t)(row0 + rr) * DFF + u.pn * HALF + wc * 32 + sl * 8;
; #pragma unroll
;         for (int ai = 0; ai < 2; ++ai)
; #pragma unroll
;             for (int m = 0; m < 4; ++m) { const int rg = ai * HALF + m * 16; const float rs = rstd_of(SS1[row0 + rg + fr]);
;                 const pg8::f32x4 g0 = acc[ai][0][m][0] * rs, g1 = acc[ai][0][m][1] * rs, u0 = acc[ai][1][m][0] * rs, u1 = acc[ai][1][m][1] * rs;
;                 u32x4 w; w.x = cvt_pk_bf16(siluf_(g0[0]) * u0[0], siluf_(g0[1]) * u0[1]); w.y = cvt_pk_bf16(siluf_(g0[2]) * u0[2], siluf_(g0[3]) * u0[3]);
;                 w.z = cvt_pk_bf16(siluf_(g1[0]) * u1[0], siluf_(g1[1]) * u1[1]); w.w = cvt_pk_bf16(siluf_(g1[2]) * u1[2], siluf_(g1[3]) * u1[3]);
;                 *(LAS u32x4*)epi_slot(W, fr, fq + 4 * (m & 1)) = w;
;                 const u32x4 o = *(const LAS u32x4*)epi_slot(W, rr, sl + 4 * (m & 1));
;                 *(u32x4*)(outp + (size_t)rg * DFF) = o; }
.LBB0_880:
	s_lshl_b32 s4, s4, 8
	s_add_i32 s21, s4, s42
	v_or_b32_e32 v148, s21, v152
	v_ashrrev_i32_e32 v149, 31, v148
	v_lshl_add_u64 v[150:151], v[148:149], 2, s[14:15]
	v_lshlrev_b32_e32 v208, 2, v152
	v_add_u32_e32 v209, 64, v208
	v_add_u32_e32 v210, 0x80, v208
	v_add_u32_e32 v211, 0xc0, v208
	ds_bpermute_b32 v200, v208, v234
	ds_bpermute_b32 v201, v209, v234
	ds_bpermute_b32 v202, v210, v234
	ds_bpermute_b32 v203, v211, v234
	ds_bpermute_b32 v204, v208, v235
	ds_bpermute_b32 v205, v209, v235
	ds_bpermute_b32 v206, v210, v235
	ds_bpermute_b32 v207, v211, v235
	v_mov_b64_e32 v[164:165], s[56:57]
	s_lshl_b32 s4, s5, 7
	s_ashr_i32 s5, s4, 31
	s_waitcnt lgkmcnt(0)
	v_fmamk_f32 v149, v200, 0x3a800000, v159
	v_rsq_f32_e32 v166, v149
	v_or_b32_e32 v149, s21, v153
	v_pk_mul_f32 v[124:125], v[124:125], v[166:167] op_sel_hi:[1,0]
	v_pk_mul_f32 v[128:129], v[128:129], v[166:167] op_sel_hi:[1,0]
	v_pk_mul_f32 v[126:127], v[126:127], v[166:167] op_sel_hi:[1,0]
	v_pk_mul_f32 v[122:123], v[122:123], v[166:167] op_sel_hi:[1,0]
	v_mul_f32_e32 v173, 0xbfb8aa3b, v125
	v_pk_mul_f32 v[120:121], v[120:121], v[166:167] op_sel_hi:[1,0]
	v_pk_mul_f32 v[118:119], v[118:119], v[166:167] op_sel_hi:[1,0]
	v_pk_mul_f32 v[116:117], v[116:117], v[166:167] op_sel_hi:[1,0]
	v_pk_mul_f32 v[114:115], v[114:115], v[166:167] op_sel_hi:[1,0]
	v_mul_f32_e32 v166, 0xbfb8aa3b, v126
	v_mul_f32_e32 v167, 0xbfb8aa3b, v127
	v_mul_f32_e32 v168, 0xbfb8aa3b, v128
	v_mul_f32_e32 v169, 0xbfb8aa3b, v129
	v_mul_f32_e32 v170, 0xbfb8aa3b, v122
	v_mul_f32_e32 v171, 0xbfb8aa3b, v123
	v_mul_f32_e32 v172, 0xbfb8aa3b, v124
	v_exp_f32_e32 v173, v173
	v_exp_f32_e32 v166, v166
	v_exp_f32_e32 v167, v167
	v_exp_f32_e32 v168, v168
	v_exp_f32_e32 v169, v169
	v_exp_f32_e32 v170, v170
	v_exp_f32_e32 v171, v171
	v_exp_f32_e32 v172, v172
	v_add_f32_e32 v173, 1.0, v173
	v_add_f32_e32 v166, 1.0, v166
	v_add_f32_e32 v167, 1.0, v167
	v_add_f32_e32 v168, 1.0, v168
	v_add_f32_e32 v169, 1.0, v169
	v_add_f32_e32 v170, 1.0, v170
	v_add_f32_e32 v171, 1.0, v171
	v_add_f32_e32 v172, 1.0, v172
	v_rcp_f32_e32 v173, v173
	v_rcp_f32_e32 v166, v166
	v_rcp_f32_e32 v167, v167
	v_rcp_f32_e32 v168, v168
	v_rcp_f32_e32 v169, v169
	v_rcp_f32_e32 v170, v170
	v_rcp_f32_e32 v171, v171
	v_rcp_f32_e32 v172, v172
	v_mul_f32_e32 v125, v125, v173
	v_mul_f32_e32 v126, v126, v166
	v_mul_f32_e32 v127, v127, v167
	v_mul_f32_e32 v128, v128, v168
	v_mul_f32_e32 v129, v129, v169
	v_mul_f32_e32 v122, v122, v170
	v_mul_f32_e32 v123, v123, v171
	v_mul_f32_e32 v124, v124, v172
	v_mul_f32_e32 v117, v117, v125
	v_mul_f32_e32 v118, v118, v126
	v_mul_f32_e32 v119, v119, v127
	v_mul_f32_e32 v120, v120, v128
	v_mul_f32_e32 v121, v121, v129
	v_mul_f32_e32 v122, v114, v122
	v_mul_f32_e32 v123, v115, v123
	v_mul_f32_e32 v124, v116, v124
	v_cvt_pk_bf16_f32 v114, v118, v119
	v_cvt_pk_bf16_f32 v115, v120, v121
	v_cvt_pk_bf16_f32 v116, v122, v123
	v_cvt_pk_bf16_f32 v117, v124, v117
	ds_write_b128 v160, v[114:117]
	ds_read_b128 v[116:119], v161
	v_mad_i64_i32 v[114:115], s[28:29], v149, s55, v[164:165]
	v_lshl_add_u64 v[114:115], s[4:5], 1, v[114:115]
	v_lshl_add_u64 v[114:115], v[114:115], 0, s[6:7]
	v_lshl_add_u64 v[114:115], v[114:115], 0, v[138:139]
	s_waitcnt lgkmcnt(0)
	global_store_dwordx4 v[114:115], v[116:119], off
	s_nop 1
	v_fmamk_f32 v116, v201, 0x3a800000, v159
	v_rsq_f32_e32 v116, v116
	s_nop 0
	v_pk_mul_f32 v[108:109], v[108:109], v[116:117] op_sel_hi:[1,0]
	v_pk_mul_f32 v[112:113], v[112:113], v[116:117] op_sel_hi:[1,0]
	v_pk_mul_f32 v[110:111], v[110:111], v[116:117] op_sel_hi:[1,0]
	v_pk_mul_f32 v[106:107], v[106:107], v[116:117] op_sel_hi:[1,0]
	v_mul_f32_e32 v123, 0xbfb8aa3b, v109
	v_pk_mul_f32 v[104:105], v[104:105], v[116:117] op_sel_hi:[1,0]
	v_pk_mul_f32 v[102:103], v[102:103], v[116:117] op_sel_hi:[1,0]
	v_pk_mul_f32 v[100:101], v[100:101], v[116:117] op_sel_hi:[1,0]
	v_pk_mul_f32 v[98:99], v[98:99], v[116:117] op_sel_hi:[1,0]
	v_mul_f32_e32 v116, 0xbfb8aa3b, v110
	v_mul_f32_e32 v117, 0xbfb8aa3b, v111
	v_mul_f32_e32 v118, 0xbfb8aa3b, v112
	v_mul_f32_e32 v119, 0xbfb8aa3b, v113
	v_mul_f32_e32 v120, 0xbfb8aa3b, v106
	v_mul_f32_e32 v121, 0xbfb8aa3b, v107
	v_mul_f32_e32 v122, 0xbfb8aa3b, v108
	v_exp_f32_e32 v123, v123
	v_exp_f32_e32 v116, v116
	v_exp_f32_e32 v117, v117
	v_exp_f32_e32 v118, v118
	v_exp_f32_e32 v119, v119
	v_exp_f32_e32 v120, v120
	v_exp_f32_e32 v121, v121
	v_exp_f32_e32 v122, v122
	v_add_f32_e32 v123, 1.0, v123
	v_add_f32_e32 v116, 1.0, v116
	v_add_f32_e32 v117, 1.0, v117
	v_add_f32_e32 v118, 1.0, v118
	v_add_f32_e32 v119, 1.0, v119
	v_add_f32_e32 v120, 1.0, v120
	v_add_f32_e32 v121, 1.0, v121
	v_add_f32_e32 v122, 1.0, v122
	v_rcp_f32_e32 v123, v123
	v_rcp_f32_e32 v116, v116
	v_rcp_f32_e32 v117, v117
	v_rcp_f32_e32 v118, v118
	v_rcp_f32_e32 v119, v119
	v_rcp_f32_e32 v120, v120
	v_rcp_f32_e32 v121, v121
	v_rcp_f32_e32 v122, v122
	v_mul_f32_e32 v109, v109, v123
	v_mul_f32_e32 v110, v110, v116
	v_mul_f32_e32 v111, v111, v117
	v_mul_f32_e32 v112, v112, v118
	v_mul_f32_e32 v113, v113, v119
	v_mul_f32_e32 v106, v106, v120
	v_mul_f32_e32 v107, v107, v121
	v_mul_f32_e32 v108, v108, v122
	v_mul_f32_e32 v101, v101, v109
	v_mul_f32_e32 v102, v102, v110
	v_mul_f32_e32 v103, v103, v111
	v_mul_f32_e32 v104, v104, v112
	v_mul_f32_e32 v105, v105, v113
	v_mul_f32_e32 v106, v98, v106
	v_mul_f32_e32 v107, v99, v107
	v_mul_f32_e32 v108, v100, v108
	v_cvt_pk_bf16_f32 v98, v102, v103
	v_cvt_pk_bf16_f32 v99, v104, v105
	v_cvt_pk_bf16_f32 v100, v106, v107
	v_cvt_pk_bf16_f32 v101, v108, v101
	ds_write_b128 v162, v[98:101]
	ds_read_b128 v[98:101], v163
	v_add_co_u32_e32 v102, vcc, s41, v114
	s_nop 1
	v_addc_co_u32_e32 v103, vcc, 0, v115, vcc
	s_waitcnt lgkmcnt(0)
; __device__ __forceinline__ unsigned cvt_pk_bf16(float lo, float hi) { unsigned r; asm volatile("v_cvt_pk_bf16_f32 %0, %1, %2" : "=v"(r) : "v"(lo), "v"(hi)); return r; }
; #define LAS __attribute__((address_space(3)))
; __device__ __forceinline__ float siluf_(float x) { return x * __builtin_amdgcn_rcpf(1.0f + __builtin_amdgcn_exp2f(-1.4426950408889634f * x)); }
; __device__ __forceinline__ float rstd_of(float ss) { return __builtin_amdgcn_rsqf(ss * (1.0f / DM) + EPS); }
;     __device__ __forceinline__ void operator()(const pg8::f32x4 (&acc)[2][2][4][2], const Unit& u, int wr, int wc, int fr, int fq) const {
;     ...
;             for (int m = 0; m < 4; ++m) { const int rg = ai * HALF + m * 16; const float rs = rstd_of(SS1[row0 + rg + fr]);
;                 const pg8::f32x4 g0 = acc[ai][0][m][0] * rs, g1 = acc[ai][0][m][1] * rs, u0 = acc[ai][1][m][0] * rs, u1 = acc[ai][1][m][1] * rs;
;                 u32x4 w; w.x = cvt_pk_bf16(siluf_(g0[0]) * u0[0], siluf_(g0[1]) * u0[1]); w.y = cvt_pk_bf16(siluf_(g0[2]) * u0[2], siluf_(g0[3]) * u0[3]);
;                 w.z = cvt_pk_bf16(siluf_(g1[0]) * u1[0], siluf_(g1[1]) * u1[1]); w.w = cvt_pk_bf16(siluf_(g1[2]) * u1[2], siluf_(g1[3]) * u1[3]);
;                 *(LAS u32x4*)epi_slot(W, fr, fq + 4 * (m & 1)) = w;
;                 const u32x4 o = *(const LAS u32x4*)epi_slot(W, rr, sl + 4 * (m & 1));
;                 *(u32x4*)(outp + (size_t)rg * DFF) = o; }
	global_store_dwordx4 v[102:103], v[98:101], off
	s_nop 1
	v_fmamk_f32 v98, v202, 0x3a800000, v159
	v_rsq_f32_e32 v98, v98
	s_nop 0
	v_pk_mul_f32 v[92:93], v[92:93], v[98:99] op_sel_hi:[1,0]
	v_pk_mul_f32 v[96:97], v[96:97], v[98:99] op_sel_hi:[1,0]
	v_pk_mul_f32 v[94:95], v[94:95], v[98:99] op_sel_hi:[1,0]
	v_pk_mul_f32 v[90:91], v[90:91], v[98:99] op_sel_hi:[1,0]
	v_mul_f32_e32 v105, 0xbfb8aa3b, v93
	v_pk_mul_f32 v[88:89], v[88:89], v[98:99] op_sel_hi:[1,0]
	v_pk_mul_f32 v[86:87], v[86:87], v[98:99] op_sel_hi:[1,0]
	v_pk_mul_f32 v[84:85], v[84:85], v[98:99] op_sel_hi:[1,0]
	v_pk_mul_f32 v[82:83], v[82:83], v[98:99] op_sel_hi:[1,0]
	v_mul_f32_e32 v98, 0xbfb8aa3b, v94
	v_mul_f32_e32 v99, 0xbfb8aa3b, v95
	v_mul_f32_e32 v100, 0xbfb8aa3b, v96
	v_mul_f32_e32 v101, 0xbfb8aa3b, v97
	v_mul_f32_e32 v102, 0xbfb8aa3b, v90
	v_mul_f32_e32 v103, 0xbfb8aa3b, v91
	v_mul_f32_e32 v104, 0xbfb8aa3b, v92
	v_exp_f32_e32 v105, v105
	v_exp_f32_e32 v98, v98
	v_exp_f32_e32 v99, v99
	v_exp_f32_e32 v100, v100
	v_exp_f32_e32 v101, v101
	v_exp_f32_e32 v102, v102
	v_exp_f32_e32 v103, v103
	v_exp_f32_e32 v104, v104
	v_add_f32_e32 v105, 1.0, v105
	v_add_f32_e32 v98, 1.0, v98
	v_add_f32_e32 v99, 1.0, v99
	v_add_f32_e32 v100, 1.0, v100
	v_add_f32_e32 v101, 1.0, v101
	v_add_f32_e32 v102, 1.0, v102
	v_add_f32_e32 v103, 1.0, v103
	v_add_f32_e32 v104, 1.0, v104
	v_rcp_f32_e32 v105, v105
	v_rcp_f32_e32 v98, v98
	v_rcp_f32_e32 v99, v99
	v_rcp_f32_e32 v100, v100
	v_rcp_f32_e32 v101, v101
	v_rcp_f32_e32 v102, v102
	v_rcp_f32_e32 v103, v103
	v_rcp_f32_e32 v104, v104
	v_mul_f32_e32 v93, v93, v105
	v_mul_f32_e32 v94, v94, v98
	v_mul_f32_e32 v95, v95, v99
	v_mul_f32_e32 v96, v96, v100
	v_mul_f32_e32 v97, v97, v101
	v_mul_f32_e32 v90, v90, v102
	v_mul_f32_e32 v91, v91, v103
	v_mul_f32_e32 v92, v92, v104
	v_mul_f32_e32 v85, v85, v93
	v_mul_f32_e32 v86, v86, v94
	v_mul_f32_e32 v87, v87, v95
	v_mul_f32_e32 v88, v88, v96
	v_mul_f32_e32 v89, v89, v97
	v_mul_f32_e32 v90, v82, v90
	v_mul_f32_e32 v91, v83, v91
	v_mul_f32_e32 v92, v84, v92
	v_cvt_pk_bf16_f32 v82, v86, v87
	v_cvt_pk_bf16_f32 v83, v88, v89
	v_cvt_pk_bf16_f32 v84, v90, v91
	v_cvt_pk_bf16_f32 v85, v92, v85
	ds_write_b128 v160, v[82:85]
	ds_read_b128 v[82:85], v161
	v_add_co_u32_e32 v86, vcc, s58, v114
	s_nop 1
	v_addc_co_u32_e32 v87, vcc, 0, v115, vcc
	s_waitcnt lgkmcnt(0)
	global_store_dwordx4 v[86:87], v[82:85], off
	s_nop 1
	v_fmamk_f32 v82, v203, 0x3a800000, v159
	v_rsq_f32_e32 v82, v82
	s_nop 0
	v_pk_mul_f32 v[76:77], v[76:77], v[82:83] op_sel_hi:[1,0]
	v_pk_mul_f32 v[80:81], v[80:81], v[82:83] op_sel_hi:[1,0]
	v_pk_mul_f32 v[78:79], v[78:79], v[82:83] op_sel_hi:[1,0]
	v_pk_mul_f32 v[74:75], v[74:75], v[82:83] op_sel_hi:[1,0]
	v_mul_f32_e32 v91, 0xbfb8aa3b, v77
	v_pk_mul_f32 v[72:73], v[72:73], v[82:83] op_sel_hi:[1,0]
	v_pk_mul_f32 v[70:71], v[70:71], v[82:83] op_sel_hi:[1,0]
	v_pk_mul_f32 v[68:69], v[68:69], v[82:83] op_sel_hi:[1,0]
	v_pk_mul_f32 v[66:67], v[66:67], v[82:83] op_sel_hi:[1,0]
	v_mul_f32_e32 v82, 0xbfb8aa3b, v78
	v_mul_f32_e32 v83, 0xbfb8aa3b, v79
	v_mul_f32_e32 v86, 0xbfb8aa3b, v80
	v_mul_f32_e32 v87, 0xbfb8aa3b, v81
	v_mul_f32_e32 v88, 0xbfb8aa3b, v74
	v_mul_f32_e32 v89, 0xbfb8aa3b, v75
	v_mul_f32_e32 v90, 0xbfb8aa3b, v76
	v_exp_f32_e32 v91, v91
	v_exp_f32_e32 v82, v82
	v_exp_f32_e32 v83, v83
	v_exp_f32_e32 v86, v86
	v_exp_f32_e32 v87, v87
	v_exp_f32_e32 v88, v88
	v_exp_f32_e32 v89, v89
	v_exp_f32_e32 v90, v90
	v_add_f32_e32 v91, 1.0, v91
	v_add_f32_e32 v82, 1.0, v82
	v_add_f32_e32 v83, 1.0, v83
	v_add_f32_e32 v86, 1.0, v86
	v_add_f32_e32 v87, 1.0, v87
	v_add_f32_e32 v88, 1.0, v88
	v_add_f32_e32 v89, 1.0, v89
	v_add_f32_e32 v90, 1.0, v90
	v_rcp_f32_e32 v91, v91
	v_rcp_f32_e32 v82, v82
	v_rcp_f32_e32 v83, v83
	v_rcp_f32_e32 v86, v86
	v_rcp_f32_e32 v87, v87
	v_rcp_f32_e32 v88, v88
	v_rcp_f32_e32 v89, v89
	v_rcp_f32_e32 v90, v90
	v_mul_f32_e32 v77, v77, v91
	v_mul_f32_e32 v78, v78, v82
	v_mul_f32_e32 v79, v79, v83
	v_mul_f32_e32 v80, v80, v86
	v_mul_f32_e32 v81, v81, v87
	v_mul_f32_e32 v74, v74, v88
	v_mul_f32_e32 v75, v75, v89
	v_mul_f32_e32 v76, v76, v90
	v_mul_f32_e32 v69, v69, v77
	v_mul_f32_e32 v70, v70, v78
	v_mul_f32_e32 v71, v71, v79
	v_mul_f32_e32 v72, v72, v80
	v_mul_f32_e32 v73, v73, v81
	v_mul_f32_e32 v74, v66, v74
	v_mul_f32_e32 v75, v67, v75
	v_mul_f32_e32 v76, v68, v76
	v_cvt_pk_bf16_f32 v66, v70, v71
	v_cvt_pk_bf16_f32 v67, v72, v73
	v_cvt_pk_bf16_f32 v68, v74, v75
	v_cvt_pk_bf16_f32 v69, v76, v69
	ds_write_b128 v162, v[66:69]
	ds_read_b128 v[66:69], v163
	v_add_co_u32_e32 v70, vcc, s59, v114
	s_nop 1
	v_addc_co_u32_e32 v71, vcc, 0, v115, vcc
	s_waitcnt lgkmcnt(0)
; __device__ __forceinline__ unsigned cvt_pk_bf16(float lo, float hi) { unsigned r; asm volatile("v_cvt_pk_bf16_f32 %0, %1, %2" : "=v"(r) : "v"(lo), "v"(hi)); return r; }
; #define LAS __attribute__((address_space(3)))
; __device__ __forceinline__ float siluf_(float x) { return x * __builtin_amdgcn_rcpf(1.0f + __builtin_amdgcn_exp2f(-1.4426950408889634f * x)); }
; __device__ __forceinline__ float rstd_of(float ss) { return __builtin_amdgcn_rsqf(ss * (1.0f / DM) + EPS); }
;     __device__ __forceinline__ void operator()(const pg8::f32x4 (&acc)[2][2][4][2], const Unit& u, int wr, int wc, int fr, int fq) const {
;     ...
;             for (int m = 0; m < 4; ++m) { const int rg = ai * HALF + m * 16; const float rs = rstd_of(SS1[row0 + rg + fr]);
;                 const pg8::f32x4 g0 = acc[ai][0][m][0] * rs, g1 = acc[ai][0][m][1] * rs, u0 = acc[ai][1][m][0] * rs, u1 = acc[ai][1][m][1] * rs;
;                 u32x4 w; w.x = cvt_pk_bf16(siluf_(g0[0]) * u0[0], siluf_(g0[1]) * u0[1]); w.y = cvt_pk_bf16(siluf_(g0[2]) * u0[2], siluf_(g0[3]) * u0[3]);
;                 w.z = cvt_pk_bf16(siluf_(g1[0]) * u1[0], siluf_(g1[1]) * u1[1]); w.w = cvt_pk_bf16(siluf_(g1[2]) * u1[2], siluf_(g1[3]) * u1[3]);
;                 *(LAS u32x4*)epi_slot(W, fr, fq + 4 * (m & 1)) = w;
;                 const u32x4 o = *(const LAS u32x4*)epi_slot(W, rr, sl + 4 * (m & 1));
;                 *(u32x4*)(outp + (size_t)rg * DFF) = o; }
	global_store_dwordx4 v[70:71], v[66:69], off
	s_nop 1
	v_fmamk_f32 v66, v204, 0x3a800000, v159
	v_rsq_f32_e32 v66, v66
	s_nop 0
	v_pk_mul_f32 v[60:61], v[60:61], v[66:67] op_sel_hi:[1,0]
	v_pk_mul_f32 v[64:65], v[64:65], v[66:67] op_sel_hi:[1,0]
	v_pk_mul_f32 v[62:63], v[62:63], v[66:67] op_sel_hi:[1,0]
	v_pk_mul_f32 v[58:59], v[58:59], v[66:67] op_sel_hi:[1,0]
	v_mul_f32_e32 v75, 0xbfb8aa3b, v61
	v_pk_mul_f32 v[56:57], v[56:57], v[66:67] op_sel_hi:[1,0]
	v_pk_mul_f32 v[54:55], v[54:55], v[66:67] op_sel_hi:[1,0]
	v_pk_mul_f32 v[52:53], v[52:53], v[66:67] op_sel_hi:[1,0]
	v_pk_mul_f32 v[50:51], v[50:51], v[66:67] op_sel_hi:[1,0]
	v_mul_f32_e32 v66, 0xbfb8aa3b, v62
	v_mul_f32_e32 v67, 0xbfb8aa3b, v63
	v_mul_f32_e32 v70, 0xbfb8aa3b, v64
	v_mul_f32_e32 v71, 0xbfb8aa3b, v65
	v_mul_f32_e32 v72, 0xbfb8aa3b, v58
	v_mul_f32_e32 v73, 0xbfb8aa3b, v59
	v_mul_f32_e32 v74, 0xbfb8aa3b, v60
	v_exp_f32_e32 v75, v75
	v_exp_f32_e32 v66, v66
	v_exp_f32_e32 v67, v67
	v_exp_f32_e32 v70, v70
	v_exp_f32_e32 v71, v71
	v_exp_f32_e32 v72, v72
	v_exp_f32_e32 v73, v73
	v_exp_f32_e32 v74, v74
	v_add_f32_e32 v75, 1.0, v75
	v_add_f32_e32 v66, 1.0, v66
	v_add_f32_e32 v67, 1.0, v67
	v_add_f32_e32 v70, 1.0, v70
	v_add_f32_e32 v71, 1.0, v71
	v_add_f32_e32 v72, 1.0, v72
	v_add_f32_e32 v73, 1.0, v73
	v_add_f32_e32 v74, 1.0, v74
	v_rcp_f32_e32 v75, v75
	v_rcp_f32_e32 v66, v66
	v_rcp_f32_e32 v67, v67
	v_rcp_f32_e32 v70, v70
	v_rcp_f32_e32 v71, v71
	v_rcp_f32_e32 v72, v72
	v_rcp_f32_e32 v73, v73
	v_rcp_f32_e32 v74, v74
	v_mul_f32_e32 v61, v61, v75
	v_mul_f32_e32 v62, v62, v66
	v_mul_f32_e32 v63, v63, v67
	v_mul_f32_e32 v64, v64, v70
	v_mul_f32_e32 v65, v65, v71
	v_mul_f32_e32 v58, v58, v72
	v_mul_f32_e32 v59, v59, v73
	v_mul_f32_e32 v60, v60, v74
	v_mul_f32_e32 v53, v53, v61
	v_mul_f32_e32 v54, v54, v62
	v_mul_f32_e32 v55, v55, v63
	v_mul_f32_e32 v56, v56, v64
	v_mul_f32_e32 v57, v57, v65
	v_mul_f32_e32 v58, v50, v58
	v_mul_f32_e32 v59, v51, v59
	v_mul_f32_e32 v60, v52, v60
	v_cvt_pk_bf16_f32 v50, v54, v55
	v_cvt_pk_bf16_f32 v51, v56, v57
	v_cvt_pk_bf16_f32 v52, v58, v59
	v_cvt_pk_bf16_f32 v53, v60, v53
	ds_write_b128 v160, v[50:53]
	ds_read_b128 v[50:53], v161
	v_add_co_u32_e32 v54, vcc, s60, v114
	s_nop 1
	v_addc_co_u32_e32 v55, vcc, 0, v115, vcc
	s_waitcnt lgkmcnt(0)
	global_store_dwordx4 v[54:55], v[50:53], off
	s_nop 1
	v_fmamk_f32 v50, v205, 0x3a800000, v159
	v_rsq_f32_e32 v50, v50
	s_nop 0
	v_pk_mul_f32 v[44:45], v[44:45], v[50:51] op_sel_hi:[1,0]
	v_pk_mul_f32 v[48:49], v[48:49], v[50:51] op_sel_hi:[1,0]
	v_pk_mul_f32 v[46:47], v[46:47], v[50:51] op_sel_hi:[1,0]
	v_pk_mul_f32 v[42:43], v[42:43], v[50:51] op_sel_hi:[1,0]
	v_mul_f32_e32 v59, 0xbfb8aa3b, v45
	v_pk_mul_f32 v[40:41], v[40:41], v[50:51] op_sel_hi:[1,0]
	v_pk_mul_f32 v[38:39], v[38:39], v[50:51] op_sel_hi:[1,0]
	v_pk_mul_f32 v[36:37], v[36:37], v[50:51] op_sel_hi:[1,0]
	v_pk_mul_f32 v[34:35], v[34:35], v[50:51] op_sel_hi:[1,0]
	v_mul_f32_e32 v50, 0xbfb8aa3b, v46
	v_mul_f32_e32 v51, 0xbfb8aa3b, v47
	v_mul_f32_e32 v54, 0xbfb8aa3b, v48
	v_mul_f32_e32 v55, 0xbfb8aa3b, v49
	v_mul_f32_e32 v56, 0xbfb8aa3b, v42
	v_mul_f32_e32 v57, 0xbfb8aa3b, v43
	v_mul_f32_e32 v58, 0xbfb8aa3b, v44
	v_exp_f32_e32 v59, v59
	v_exp_f32_e32 v50, v50
	v_exp_f32_e32 v51, v51
	v_exp_f32_e32 v54, v54
	v_exp_f32_e32 v55, v55
	v_exp_f32_e32 v56, v56
	v_exp_f32_e32 v57, v57
	v_exp_f32_e32 v58, v58
	v_add_f32_e32 v59, 1.0, v59
	v_add_f32_e32 v50, 1.0, v50
	v_add_f32_e32 v51, 1.0, v51
	v_add_f32_e32 v54, 1.0, v54
	v_add_f32_e32 v55, 1.0, v55
	v_add_f32_e32 v56, 1.0, v56
	v_add_f32_e32 v57, 1.0, v57
	v_add_f32_e32 v58, 1.0, v58
	v_rcp_f32_e32 v59, v59
	v_rcp_f32_e32 v50, v50
	v_rcp_f32_e32 v51, v51
	v_rcp_f32_e32 v54, v54
	v_rcp_f32_e32 v55, v55
	v_rcp_f32_e32 v56, v56
	v_rcp_f32_e32 v57, v57
	v_rcp_f32_e32 v58, v58
	v_mul_f32_e32 v45, v45, v59
	v_mul_f32_e32 v46, v46, v50
	v_mul_f32_e32 v47, v47, v51
	v_mul_f32_e32 v48, v48, v54
	v_mul_f32_e32 v49, v49, v55
	v_mul_f32_e32 v42, v42, v56
	v_mul_f32_e32 v43, v43, v57
	v_mul_f32_e32 v44, v44, v58
	v_mul_f32_e32 v37, v37, v45
	v_mul_f32_e32 v38, v38, v46
	v_mul_f32_e32 v39, v39, v47
	v_mul_f32_e32 v40, v40, v48
	v_mul_f32_e32 v41, v41, v49
	v_mul_f32_e32 v42, v34, v42
	v_mul_f32_e32 v43, v35, v43
	v_mul_f32_e32 v44, v36, v44
	v_cvt_pk_bf16_f32 v34, v38, v39
	v_cvt_pk_bf16_f32 v35, v40, v41
	v_cvt_pk_bf16_f32 v36, v42, v43
	v_cvt_pk_bf16_f32 v37, v44, v37
	ds_write_b128 v162, v[34:37]
	ds_read_b128 v[34:37], v163
	v_add_co_u32_e32 v38, vcc, s61, v114
	s_nop 1
	v_addc_co_u32_e32 v39, vcc, 0, v115, vcc
	s_waitcnt lgkmcnt(0)
; __device__ __forceinline__ unsigned cvt_pk_bf16(float lo, float hi) { unsigned r; asm volatile("v_cvt_pk_bf16_f32 %0, %1, %2" : "=v"(r) : "v"(lo), "v"(hi)); return r; }
; #define LAS __attribute__((address_space(3)))
; __device__ __forceinline__ float siluf_(float x) { return x * __builtin_amdgcn_rcpf(1.0f + __builtin_amdgcn_exp2f(-1.4426950408889634f * x)); }
; __device__ __forceinline__ float rstd_of(float ss) { return __builtin_amdgcn_rsqf(ss * (1.0f / DM) + EPS); }
;     __device__ __forceinline__ void operator()(const pg8::f32x4 (&acc)[2][2][4][2], const Unit& u, int wr, int wc, int fr, int fq) const {
;     ...
;             for (int m = 0; m < 4; ++m) { const int rg = ai * HALF + m * 16; const float rs = rstd_of(SS1[row0 + rg + fr]);
;                 const pg8::f32x4 g0 = acc[ai][0][m][0] * rs, g1 = acc[ai][0][m][1] * rs, u0 = acc[ai][1][m][0] * rs, u1 = acc[ai][1][m][1] * rs;
;                 u32x4 w; w.x = cvt_pk_bf16(siluf_(g0[0]) * u0[0], siluf_(g0[1]) * u0[1]); w.y = cvt_pk_bf16(siluf_(g0[2]) * u0[2], siluf_(g0[3]) * u0[3]);
;                 w.z = cvt_pk_bf16(siluf_(g1[0]) * u1[0], siluf_(g1[1]) * u1[1]); w.w = cvt_pk_bf16(siluf_(g1[2]) * u1[2], siluf_(g1[3]) * u1[3]);
;                 *(LAS u32x4*)epi_slot(W, fr, fq + 4 * (m & 1)) = w;
;                 const u32x4 o = *(const LAS u32x4*)epi_slot(W, rr, sl + 4 * (m & 1));
;                 *(u32x4*)(outp + (size_t)rg * DFF) = o; }
	global_store_dwordx4 v[38:39], v[34:37], off
	s_nop 1
	v_fmamk_f32 v34, v206, 0x3a800000, v159
	v_rsq_f32_e32 v34, v34
	s_nop 0
	v_pk_mul_f32 v[28:29], v[28:29], v[34:35] op_sel_hi:[1,0]
	v_pk_mul_f32 v[32:33], v[32:33], v[34:35] op_sel_hi:[1,0]
	v_pk_mul_f32 v[30:31], v[30:31], v[34:35] op_sel_hi:[1,0]
	v_pk_mul_f32 v[26:27], v[26:27], v[34:35] op_sel_hi:[1,0]
	v_mul_f32_e32 v43, 0xbfb8aa3b, v29
	v_pk_mul_f32 v[24:25], v[24:25], v[34:35] op_sel_hi:[1,0]
	v_pk_mul_f32 v[22:23], v[22:23], v[34:35] op_sel_hi:[1,0]
	v_pk_mul_f32 v[20:21], v[20:21], v[34:35] op_sel_hi:[1,0]
	v_pk_mul_f32 v[18:19], v[18:19], v[34:35] op_sel_hi:[1,0]
	v_mul_f32_e32 v34, 0xbfb8aa3b, v30
	v_mul_f32_e32 v35, 0xbfb8aa3b, v31
	v_mul_f32_e32 v38, 0xbfb8aa3b, v32
	v_mul_f32_e32 v39, 0xbfb8aa3b, v33
	v_mul_f32_e32 v40, 0xbfb8aa3b, v26
	v_mul_f32_e32 v41, 0xbfb8aa3b, v27
	v_mul_f32_e32 v42, 0xbfb8aa3b, v28
	v_exp_f32_e32 v43, v43
	v_exp_f32_e32 v34, v34
	v_exp_f32_e32 v35, v35
	v_exp_f32_e32 v38, v38
	v_exp_f32_e32 v39, v39
	v_exp_f32_e32 v40, v40
	v_exp_f32_e32 v41, v41
	v_exp_f32_e32 v42, v42
	v_add_f32_e32 v43, 1.0, v43
	v_add_f32_e32 v34, 1.0, v34
	v_add_f32_e32 v35, 1.0, v35
	v_add_f32_e32 v38, 1.0, v38
	v_add_f32_e32 v39, 1.0, v39
	v_add_f32_e32 v40, 1.0, v40
	v_add_f32_e32 v41, 1.0, v41
	v_add_f32_e32 v42, 1.0, v42
	v_rcp_f32_e32 v43, v43
	v_rcp_f32_e32 v34, v34
	v_rcp_f32_e32 v35, v35
	v_rcp_f32_e32 v38, v38
	v_rcp_f32_e32 v39, v39
	v_rcp_f32_e32 v40, v40
	v_rcp_f32_e32 v41, v41
	v_rcp_f32_e32 v42, v42
	v_mul_f32_e32 v29, v29, v43
	v_mul_f32_e32 v30, v30, v34
	v_mul_f32_e32 v31, v31, v35
	v_mul_f32_e32 v32, v32, v38
	v_mul_f32_e32 v33, v33, v39
	v_mul_f32_e32 v26, v26, v40
	v_mul_f32_e32 v27, v27, v41
	v_mul_f32_e32 v28, v28, v42
	v_mul_f32_e32 v21, v21, v29
	v_mul_f32_e32 v22, v22, v30
	v_mul_f32_e32 v23, v23, v31
	v_mul_f32_e32 v24, v24, v32
	v_mul_f32_e32 v25, v25, v33
	v_mul_f32_e32 v26, v18, v26
	v_mul_f32_e32 v27, v19, v27
	v_mul_f32_e32 v28, v20, v28
	v_cvt_pk_bf16_f32 v18, v22, v23
	v_cvt_pk_bf16_f32 v19, v24, v25
	v_cvt_pk_bf16_f32 v20, v26, v27
	v_cvt_pk_bf16_f32 v21, v28, v21
	ds_write_b128 v160, v[18:21]
	ds_read_b128 v[18:21], v161
	v_add_co_u32_e32 v22, vcc, s62, v114
	s_nop 1
	v_addc_co_u32_e32 v23, vcc, 0, v115, vcc
	s_waitcnt lgkmcnt(0)
	global_store_dwordx4 v[22:23], v[18:21], off
	s_nop 1
	v_add_co_u32_e32 v20, vcc, 0xf2000, v114
	v_fmamk_f32 v18, v207, 0x3a800000, v159
	v_rsq_f32_e32 v18, v18
	s_nop 0
	v_pk_mul_f32 v[12:13], v[12:13], v[18:19] op_sel_hi:[1,0]
	v_pk_mul_f32 v[16:17], v[16:17], v[18:19] op_sel_hi:[1,0]
	v_pk_mul_f32 v[14:15], v[14:15], v[18:19] op_sel_hi:[1,0]
	v_pk_mul_f32 v[10:11], v[10:11], v[18:19] op_sel_hi:[1,0]
	v_mul_f32_e32 v26, 0xbfb8aa3b, v13
	v_pk_mul_f32 v[8:9], v[8:9], v[18:19] op_sel_hi:[1,0]
	v_pk_mul_f32 v[6:7], v[6:7], v[18:19] op_sel_hi:[1,0]
	v_pk_mul_f32 v[4:5], v[4:5], v[18:19] op_sel_hi:[1,0]
	v_pk_mul_f32 v[2:3], v[2:3], v[18:19] op_sel_hi:[1,0]
	v_mul_f32_e32 v18, 0xbfb8aa3b, v14
	v_mul_f32_e32 v19, 0xbfb8aa3b, v15
	v_mul_f32_e32 v21, 0xbfb8aa3b, v16
	v_mul_f32_e32 v22, 0xbfb8aa3b, v17
	v_mul_f32_e32 v23, 0xbfb8aa3b, v10
	v_mul_f32_e32 v24, 0xbfb8aa3b, v11
	v_mul_f32_e32 v25, 0xbfb8aa3b, v12
	v_exp_f32_e32 v26, v26
	v_exp_f32_e32 v18, v18
	v_exp_f32_e32 v19, v19
	v_exp_f32_e32 v21, v21
	v_exp_f32_e32 v22, v22
	v_exp_f32_e32 v23, v23
	v_exp_f32_e32 v24, v24
	v_exp_f32_e32 v25, v25
	v_add_f32_e32 v26, 1.0, v26
	v_add_f32_e32 v18, 1.0, v18
	v_add_f32_e32 v19, 1.0, v19
	v_add_f32_e32 v21, 1.0, v21
	v_add_f32_e32 v22, 1.0, v22
	v_add_f32_e32 v23, 1.0, v23
	v_add_f32_e32 v24, 1.0, v24
	v_add_f32_e32 v25, 1.0, v25
	v_rcp_f32_e32 v26, v26
	v_rcp_f32_e32 v18, v18
	v_rcp_f32_e32 v19, v19
	v_rcp_f32_e32 v21, v21
	v_rcp_f32_e32 v22, v22
	v_rcp_f32_e32 v23, v23
	v_rcp_f32_e32 v24, v24
	v_rcp_f32_e32 v25, v25
	v_mul_f32_e32 v13, v13, v26
	v_mul_f32_e32 v14, v14, v18
	v_mul_f32_e32 v15, v15, v19
	v_mul_f32_e32 v16, v16, v21
	v_mul_f32_e32 v17, v17, v22
	v_mul_f32_e32 v10, v10, v23
	v_mul_f32_e32 v11, v11, v24
	v_mul_f32_e32 v12, v12, v25
	v_mul_f32_e32 v5, v5, v13
	v_mul_f32_e32 v6, v6, v14
	v_mul_f32_e32 v7, v7, v15
	v_mul_f32_e32 v8, v8, v16
	v_mul_f32_e32 v9, v9, v17
	v_mul_f32_e32 v10, v2, v10
	v_mul_f32_e32 v11, v3, v11
	v_mul_f32_e32 v12, v4, v12
	v_cvt_pk_bf16_f32 v2, v6, v7
	v_cvt_pk_bf16_f32 v3, v8, v9
	v_cvt_pk_bf16_f32 v4, v10, v11
	v_cvt_pk_bf16_f32 v5, v12, v5
	ds_write_b128 v162, v[2:5]
	ds_read_b128 v[2:5], v163
	v_addc_co_u32_e32 v21, vcc, 0, v115, vcc
	s_andn2_b64 vcc, exec, s[0:1]
	s_mov_b64 s[0:1], -1
	s_waitcnt lgkmcnt(0)
	global_store_dwordx4 v[20:21], v[2:5], off
	s_cbranch_vccnz .LBB0_873
	s_andn2_b64 vcc, exec, s[12:13]
	s_cbranch_vccnz .LBB0_872
	s_barrier
	s_branch .LBB0_872
